# G2 scan loop reschedule: vb0 before vb1 in ATT round, Sb2/Sb3 packing deferred to next step round 1, next-chunk LDS addresses computed in tail
# speedup vs baseline: 1.0215x; 1.0215x over previous
.LBB0_1545:
	s_ashr_i32 s0, s42, 2
	s_and_b32 s0, s0, -8
	s_and_b32 s1, s42, 7
	s_or_b32 s0, s0, s1
	s_cmp_gt_i32 s0, 11
	s_cbranch_scc1 .LBB0_1544
	s_mul_hi_i32 s4, s0, 0x2aaaaaab
	s_lshr_b32 s1, s4, 31
	s_add_i32 s4, s4, s1
	s_mul_i32 s1, s4, 6
	s_lshr_b32 s12, s42, 3
	s_sub_i32 s5, s0, s1
	s_mov_b64 s[0:1], -1
	s_and_b64 vcc, exec, s[10:11]
	s_cbranch_vccz .LBB0_1550
	s_and_b32 s0, s12, 3
	s_waitcnt vmcnt(10)
	v_lshl_or_b32 v0, s0, 7, v126
	s_lshl_b32 s0, s5, 7
	s_ashr_i32 s1, s0, 31
	s_mul_i32 s9, s4, 0x6800000
	s_lshl_b64 s[0:1], s[0:1], 1
	s_mul_hi_i32 s8, s4, 0x6800000
	s_add_u32 s0, s0, s9
	s_addc_u32 s1, s1, s8
	v_lshrrev_b32_e32 v2, 3, v0
	v_mov_b64_e32 v[0:1], s[0:1]
	s_movk_i32 s0, 0x1a00
	v_mad_u64_u32 v[0:1], s[0:1], v2, s0, v[0:1]
	s_waitcnt vmcnt(1)
	v_lshl_add_u64 v[48:49], v[122:123], 0, v[0:1]
	v_mov_b32_e32 v0, 0
	s_mov_b32 s0, 0
	v_mov_b32_e32 v32, 0
	v_mov_b32_e32 v33, 0
	v_mov_b32_e32 v34, 0
	v_mov_b32_e32 v35, 0
	v_mov_b32_e32 v36, 0
	v_mov_b32_e32 v37, 0
	v_mov_b32_e32 v38, 0
	v_mov_b32_e32 v39, 0
	v_mov_b32_e32 v40, 0
	v_mov_b32_e32 v41, 0
	v_mov_b32_e32 v42, 0
	v_mov_b32_e32 v43, 0
	v_mov_b32_e32 v44, 0
	v_mov_b32_e32 v45, 0
	v_mov_b32_e32 v46, 0
	v_mov_b32_e32 v47, 0
	v_mov_b32_e32 v1, v0
	v_mov_b32_e32 v2, v0
	v_mov_b32_e32 v3, v0
	v_mov_b32_e32 v4, v0
	v_mov_b32_e32 v5, v0
	v_mov_b32_e32 v6, v0
	v_mov_b32_e32 v7, v0
	v_mov_b32_e32 v8, v0
	v_mov_b32_e32 v9, v0
	v_mov_b32_e32 v10, v0
	v_mov_b32_e32 v11, v0
	v_mov_b32_e32 v12, v0
	v_mov_b32_e32 v13, v0
	v_mov_b32_e32 v14, v0
	v_mov_b32_e32 v15, v0
	v_mov_b32_e32 v16, v0
	v_mov_b32_e32 v17, v0
	v_mov_b32_e32 v18, v0
	v_mov_b32_e32 v19, v0
	v_mov_b32_e32 v20, v0
	v_mov_b32_e32 v21, v0
	v_mov_b32_e32 v22, v0
	v_mov_b32_e32 v23, v0
	v_mov_b32_e32 v24, v0
	v_mov_b32_e32 v25, v0
	v_mov_b32_e32 v26, v0
	v_mov_b32_e32 v27, v0
	v_mov_b32_e32 v28, v0
	v_mov_b32_e32 v29, v0
	v_mov_b32_e32 v30, v0
	v_mov_b32_e32 v31, v0
	v_mov_b32_e32 v51, v120
	v_add_u32_e32 v50, s79, v124
	v_mov_b32_e32 v214, 0x20000
	s_waitcnt vmcnt(0)
	s_barrier
.LBB0_1548:
	ds_read_b128 v[52:55], v51 offset:0
	ds_read_b128 v[56:59], v51 offset:16384
	ds_read_b128 v[60:63], v51 offset:4096
	ds_read_b128 v[64:67], v51 offset:20480
	ds_read_b128 v[68:71], v51 offset:8192
	ds_read_b128 v[72:75], v51 offset:24576
	ds_read_b128 v[76:79], v51 offset:12288
	ds_read_b128 v[80:83], v51 offset:28672
	ds_read_b128 v[116:119], v50 offset:57344
	ds_read_b128 v[208:211], v50 offset:57360
	ds_read_b32 v212, v214
	ds_read_b128 v[84:87], v51 offset:1024
	ds_read_b128 v[88:91], v51 offset:17408
	ds_read_b128 v[92:95], v51 offset:5120
	ds_read_b128 v[96:99], v51 offset:21504
	s_waitcnt lgkmcnt(14)
	v_mfma_f32_16x16x32_bf16 v[176:179], v[52:55], v[44:47], 0
	ds_read_b128 v[100:103], v51 offset:9216
	v_cvt_pk_bf16_f32 v36, v16, v17
	v_cvt_pk_bf16_f32 v37, v18, v19
	s_waitcnt lgkmcnt(14)
	v_mfma_f32_16x16x32_bf16 v[192:195], v[56:59], v[44:47], 0
	ds_read_b128 v[104:107], v51 offset:25600
	v_cvt_pk_bf16_f32 v38, v20, v21
	v_cvt_pk_bf16_f32 v39, v22, v23
	s_waitcnt lgkmcnt(14)
	v_mfma_f32_16x16x32_bf16 v[180:183], v[60:63], v[44:47], 0
	ds_read_b128 v[108:111], v51 offset:13312
	v_cvt_pk_bf16_f32 v32, v24, v25
	v_cvt_pk_bf16_f32 v33, v26, v27
	s_waitcnt lgkmcnt(14)
	v_mfma_f32_16x16x32_bf16 v[196:199], v[64:67], v[44:47], 0
	ds_read_b128 v[112:115], v51 offset:29696
	v_cvt_pk_bf16_f32 v34, v28, v29
	v_cvt_pk_bf16_f32 v35, v30, v31
	s_waitcnt lgkmcnt(14)
	v_mfma_f32_16x16x32_bf16 v[184:187], v[68:71], v[44:47], 0
	s_waitcnt lgkmcnt(10)
	v_lshlrev_b32_e32 v232, 16, v116
	v_and_b32_e32 v233, 0xffff0000, v116
	v_mfma_f32_16x16x32_bf16 v[200:203], v[72:75], v[44:47], 0
	v_lshlrev_b32_e32 v234, 16, v117
	v_and_b32_e32 v235, 0xffff0000, v117
	v_mfma_f32_16x16x32_bf16 v[188:191], v[76:79], v[44:47], 0
	v_lshlrev_b32_e32 v236, 16, v118
	v_and_b32_e32 v237, 0xffff0000, v118
	v_mfma_f32_16x16x32_bf16 v[204:207], v[80:83], v[44:47], 0
	v_lshlrev_b32_e32 v238, 16, v119
	v_and_b32_e32 v239, 0xffff0000, v119
	ds_read_b128 v[128:131], v51 offset:2048
	ds_read_b128 v[132:135], v51 offset:18432
	ds_read_b128 v[136:139], v51 offset:6144
	ds_read_b128 v[140:143], v51 offset:22528
	s_waitcnt lgkmcnt(11)
	v_mfma_f32_16x16x32_bf16 v[176:179], v[84:87], v[40:43], v[176:179]
	ds_read_b128 v[144:147], v51 offset:10240
	v_lshlrev_b32_e32 v240, 16, v208
	v_and_b32_e32 v241, 0xffff0000, v208
	s_waitcnt lgkmcnt(11)
	v_mfma_f32_16x16x32_bf16 v[192:195], v[88:91], v[40:43], v[192:195]
	ds_read_b128 v[148:151], v51 offset:26624
	v_lshlrev_b32_e32 v242, 16, v209
	v_and_b32_e32 v243, 0xffff0000, v209
	s_waitcnt lgkmcnt(11)
	v_mfma_f32_16x16x32_bf16 v[180:183], v[92:95], v[40:43], v[180:183]
	ds_read_b128 v[152:155], v51 offset:14336
	v_lshlrev_b32_e32 v244, 16, v210
	v_and_b32_e32 v245, 0xffff0000, v210
	s_waitcnt lgkmcnt(11)
	v_mfma_f32_16x16x32_bf16 v[196:199], v[96:99], v[40:43], v[196:199]
	ds_read_b128 v[156:159], v51 offset:30720
	v_lshlrev_b32_e32 v246, 16, v211
	v_and_b32_e32 v247, 0xffff0000, v211
	s_waitcnt lgkmcnt(11)
	v_mfma_f32_16x16x32_bf16 v[184:187], v[100:103], v[40:43], v[184:187]
	v_mul_f32_e32 v0, v212, v0
	v_mul_f32_e32 v1, v212, v1
	s_waitcnt lgkmcnt(10)
	v_mfma_f32_16x16x32_bf16 v[200:203], v[104:107], v[40:43], v[200:203]
	v_mul_f32_e32 v2, v212, v2
	v_mul_f32_e32 v3, v212, v3
	s_waitcnt lgkmcnt(9)
	v_mfma_f32_16x16x32_bf16 v[188:191], v[108:111], v[40:43], v[188:191]
	v_mul_f32_e32 v4, v212, v4
	v_mul_f32_e32 v5, v212, v5
	s_waitcnt lgkmcnt(8)
	v_mfma_f32_16x16x32_bf16 v[204:207], v[112:115], v[40:43], v[204:207]
	v_mul_f32_e32 v6, v212, v6
	v_mul_f32_e32 v7, v212, v7
	ds_read_b128 v[52:55], v51 offset:3072
	ds_read_b128 v[56:59], v51 offset:7168
	ds_read_b128 v[60:63], v51 offset:11264
	ds_read_b128 v[64:67], v51 offset:15360
	s_waitcnt lgkmcnt(11)
	v_mfma_f32_16x16x32_bf16 v[176:179], v[128:131], v[36:39], v[176:179]
	ds_read_b128 v[68:71], v51 offset:19456
	v_mul_f32_e32 v8, v212, v8
	v_mul_f32_e32 v9, v212, v9
	s_waitcnt lgkmcnt(11)
	v_mfma_f32_16x16x32_bf16 v[192:195], v[132:135], v[36:39], v[192:195]
	ds_read_b128 v[72:75], v51 offset:23552
	v_mul_f32_e32 v10, v212, v10
	v_mul_f32_e32 v11, v212, v11
	s_waitcnt lgkmcnt(11)
	v_mfma_f32_16x16x32_bf16 v[180:183], v[136:139], v[36:39], v[180:183]
	ds_read_b128 v[76:79], v51 offset:27648
	v_mul_f32_e32 v12, v212, v12
	v_mul_f32_e32 v13, v212, v13
	s_waitcnt lgkmcnt(11)
	v_mfma_f32_16x16x32_bf16 v[196:199], v[140:143], v[36:39], v[196:199]
	ds_read_b128 v[80:83], v51 offset:31744
	v_mul_f32_e32 v14, v212, v14
	v_mul_f32_e32 v15, v212, v15
	s_waitcnt lgkmcnt(11)
	v_mfma_f32_16x16x32_bf16 v[184:187], v[144:147], v[36:39], v[184:187]
	v_mul_f32_e32 v16, v212, v16
	v_mul_f32_e32 v17, v212, v17
	s_waitcnt lgkmcnt(10)
	v_mfma_f32_16x16x32_bf16 v[200:203], v[148:151], v[36:39], v[200:203]
	v_mul_f32_e32 v18, v212, v18
	v_mul_f32_e32 v19, v212, v19
	s_waitcnt lgkmcnt(9)
	v_mfma_f32_16x16x32_bf16 v[188:191], v[152:155], v[36:39], v[188:191]
	v_mul_f32_e32 v20, v212, v20
	v_mul_f32_e32 v21, v212, v21
	s_waitcnt lgkmcnt(8)
	v_mfma_f32_16x16x32_bf16 v[204:207], v[156:159], v[36:39], v[204:207]
	v_mul_f32_e32 v22, v212, v22
	v_mul_f32_e32 v23, v212, v23
	ds_read_b128 v[84:87], v51 offset:49152
	ds_read_b128 v[88:91], v51 offset:51200
	ds_read_b128 v[92:95], v51 offset:53248
	ds_read_b128 v[96:99], v51 offset:55296
	s_waitcnt lgkmcnt(11)
	v_mfma_f32_16x16x32_bf16 v[176:179], v[52:55], v[32:35], v[176:179]
	ds_read_b128 v[100:103], v51 offset:50176
	v_mul_f32_e32 v24, v212, v24
	v_mul_f32_e32 v25, v212, v25
	s_waitcnt lgkmcnt(11)
	v_mfma_f32_16x16x32_bf16 v[180:183], v[56:59], v[32:35], v[180:183]
	ds_read_b128 v[104:107], v51 offset:52224
	v_mul_f32_e32 v26, v212, v26
	v_mul_f32_e32 v27, v212, v27
	s_waitcnt lgkmcnt(11)
	v_mfma_f32_16x16x32_bf16 v[184:187], v[60:63], v[32:35], v[184:187]
	ds_read_b128 v[108:111], v51 offset:54272
	v_mul_f32_e32 v28, v212, v28
	v_mul_f32_e32 v29, v212, v29
	s_waitcnt lgkmcnt(11)
	v_mfma_f32_16x16x32_bf16 v[188:191], v[64:67], v[32:35], v[188:191]
	ds_read_b128 v[112:115], v51 offset:56320
	v_mul_f32_e32 v30, v212, v30
	v_mul_f32_e32 v31, v212, v31
	s_waitcnt lgkmcnt(11)
	v_mfma_f32_16x16x32_bf16 v[192:195], v[68:71], v[32:35], v[192:195]
	v_sub_f32_e32 v232, v232, v176
	v_sub_f32_e32 v233, v233, v177
	v_sub_f32_e32 v234, v234, v178
	v_sub_f32_e32 v235, v235, v179
	s_waitcnt lgkmcnt(10)
	v_mfma_f32_16x16x32_bf16 v[196:199], v[72:75], v[32:35], v[196:199]
	v_sub_f32_e32 v236, v236, v180
	v_sub_f32_e32 v237, v237, v181
	v_sub_f32_e32 v238, v238, v182
	v_sub_f32_e32 v239, v239, v183
	s_waitcnt lgkmcnt(9)
	v_mfma_f32_16x16x32_bf16 v[200:203], v[76:79], v[32:35], v[200:203]
	v_cvt_pk_bf16_f32 v216, v232, v233
	v_cvt_pk_bf16_f32 v217, v234, v235
	v_cvt_pk_bf16_f32 v218, v236, v237
	v_cvt_pk_bf16_f32 v219, v238, v239
	s_waitcnt lgkmcnt(8)
	v_mfma_f32_16x16x32_bf16 v[204:207], v[80:83], v[32:35], v[204:207]
	v_sub_f32_e32 v240, v240, v184
	v_sub_f32_e32 v241, v241, v185
	v_sub_f32_e32 v242, v242, v186
	v_sub_f32_e32 v243, v243, v187
	v_sub_f32_e32 v244, v244, v188
	v_sub_f32_e32 v245, v245, v189
	v_sub_f32_e32 v246, v246, v190
	v_sub_f32_e32 v247, v247, v191
	ds_read_b128 v[128:131], v51 offset:32768
	ds_read_b128 v[132:135], v51 offset:33792
	ds_read_b128 v[136:139], v51 offset:34816
	ds_read_b128 v[140:143], v51 offset:35840
	ds_read_b128 v[144:147], v51 offset:36864
	ds_read_b128 v[148:151], v51 offset:37888
	s_waitcnt lgkmcnt(13)
	v_mfma_f32_16x16x32_bf16 v[192:195], v[84:87], v[216:219], v[192:195]
	v_cvt_pk_bf16_f32 v220, v240, v241
	v_cvt_pk_bf16_f32 v221, v242, v243
	s_waitcnt lgkmcnt(12)
	v_mfma_f32_16x16x32_bf16 v[196:199], v[88:91], v[216:219], v[196:199]
	v_cvt_pk_bf16_f32 v222, v244, v245
	v_cvt_pk_bf16_f32 v223, v246, v247
	s_waitcnt lgkmcnt(11)
	v_mfma_f32_16x16x32_bf16 v[200:203], v[92:95], v[216:219], v[200:203]
	ds_read_b128 v[152:155], v51 offset:38912
	s_waitcnt lgkmcnt(11)
	v_mfma_f32_16x16x32_bf16 v[204:207], v[96:99], v[216:219], v[204:207]
	ds_read_b128 v[156:159], v51 offset:39936
	s_waitcnt lgkmcnt(11)
	v_mfma_f32_16x16x32_bf16 v[192:195], v[100:103], v[220:223], v[192:195]
	s_waitcnt lgkmcnt(10)
	v_mfma_f32_16x16x32_bf16 v[196:199], v[104:107], v[220:223], v[196:199]
	s_waitcnt lgkmcnt(9)
	v_mfma_f32_16x16x32_bf16 v[200:203], v[108:111], v[220:223], v[200:203]
	s_waitcnt lgkmcnt(8)
	v_mfma_f32_16x16x32_bf16 v[204:207], v[112:115], v[220:223], v[204:207]
	ds_read_b128 v[52:55], v51 offset:40960
	ds_read_b128 v[56:59], v51 offset:41984
	ds_read_b128 v[60:63], v51 offset:43008
	ds_read_b128 v[64:67], v51 offset:44032
	ds_read_b128 v[68:71], v51 offset:45056
	ds_read_b128 v[72:75], v51 offset:46080
	ds_read_b128 v[76:79], v51 offset:47104
	s_waitcnt lgkmcnt(14)
	v_mfma_f32_16x16x32_bf16 v[0:3], v[128:131], v[216:219], v[0:3]
	ds_read_b128 v[80:83], v51 offset:48128
	s_waitcnt lgkmcnt(14)
	v_mfma_f32_16x16x32_bf16 v[0:3], v[132:135], v[220:223], v[0:3]
	s_waitcnt lgkmcnt(13)
	v_mfma_f32_16x16x32_bf16 v[4:7], v[136:139], v[216:219], v[4:7]
	s_waitcnt lgkmcnt(12)
	v_mfma_f32_16x16x32_bf16 v[4:7], v[140:143], v[220:223], v[4:7]
	s_waitcnt lgkmcnt(11)
	v_mfma_f32_16x16x32_bf16 v[8:11], v[144:147], v[216:219], v[8:11]
	s_waitcnt lgkmcnt(10)
	v_mfma_f32_16x16x32_bf16 v[8:11], v[148:151], v[220:223], v[8:11]
	v_cvt_pk_bf16_f32 v224, v192, v193
	v_cvt_pk_bf16_f32 v225, v194, v195
	v_cvt_pk_bf16_f32 v226, v196, v197
	v_cvt_pk_bf16_f32 v227, v198, v199
	s_waitcnt lgkmcnt(9)
	v_mfma_f32_16x16x32_bf16 v[12:15], v[152:155], v[216:219], v[12:15]
	s_waitcnt lgkmcnt(8)
	v_mfma_f32_16x16x32_bf16 v[12:15], v[156:159], v[220:223], v[12:15]
	v_cvt_pk_bf16_f32 v228, v200, v201
	v_cvt_pk_bf16_f32 v229, v202, v203
	v_cvt_pk_bf16_f32 v230, v204, v205
	v_cvt_pk_bf16_f32 v231, v206, v207
	global_store_dwordx4 v[48:49], v[224:227], off
	global_store_dwordx4 v[48:49], v[228:231], off offset:16
	s_add_i32 s0, s0, 1
	s_and_b32 s1, s0, 1
	s_lshl_b32 s8, s1, 16
	s_lshl_b32 s1, s1, 2
	s_add_i32 s9, s8, s79
	s_add_i32 s1, s1, 0x20000
	s_waitcnt lgkmcnt(7)
	v_mfma_f32_16x16x32_bf16 v[16:19], v[52:55], v[216:219], v[16:19]
	s_waitcnt lgkmcnt(6)
	v_mfma_f32_16x16x32_bf16 v[16:19], v[56:59], v[220:223], v[16:19]
	v_cvt_pk_bf16_f32 v44, v0, v1
	v_cvt_pk_bf16_f32 v45, v2, v3
	s_waitcnt lgkmcnt(5)
	v_mfma_f32_16x16x32_bf16 v[20:23], v[60:63], v[216:219], v[20:23]
	s_waitcnt lgkmcnt(4)
	v_mfma_f32_16x16x32_bf16 v[20:23], v[64:67], v[220:223], v[20:23]
	v_cvt_pk_bf16_f32 v46, v4, v5
	v_cvt_pk_bf16_f32 v47, v6, v7
	v_add_u32_e32 v51, s8, v120
	s_waitcnt lgkmcnt(3)
	v_mfma_f32_16x16x32_bf16 v[24:27], v[68:71], v[216:219], v[24:27]
	s_waitcnt lgkmcnt(2)
	v_mfma_f32_16x16x32_bf16 v[24:27], v[72:75], v[220:223], v[24:27]
	v_cvt_pk_bf16_f32 v40, v8, v9
	v_cvt_pk_bf16_f32 v41, v10, v11
	v_add_u32_e32 v50, s9, v124
	v_mov_b32_e32 v214, s1
	s_mov_b64 s[8:9], 0x68000
	v_cvt_pk_bf16_f32 v42, v12, v13
	v_cvt_pk_bf16_f32 v43, v14, v15
	v_lshl_add_u64 v[48:49], v[48:49], 0, s[8:9]
	s_waitcnt lgkmcnt(1)
	v_mfma_f32_16x16x32_bf16 v[28:31], v[76:79], v[216:219], v[28:31]
	s_waitcnt lgkmcnt(0)
	v_mfma_f32_16x16x32_bf16 v[28:31], v[80:83], v[220:223], v[28:31]
	s_cmpk_lg_i32 s0, 0x100
	s_barrier
	s_cbranch_scc1 .LBB0_1548
	s_mov_b64 s[0:1], 0
